# speedup vs baseline: 1.0054x; 1.0054x over previous
; __device__ __forceinline__ u32 pack2(float a, float b) { return (u32)f2bf(a) | ((u32)f2bf(b) << 16); }
; __device__ __forceinline__ float sigmoidf_(float x) { return __builtin_amdgcn_rcpf(1.f + __expf(-x)); }
; __device__ __forceinline__ void gemm_tile(const GemmArgs& ga, int wgid, int next_wgid, bool prefetched, u16* shm, unsigned char* ws, int wv_) {
;     ...
;   if (epi == EPI_SWIGLU) {
;     const int oc = pn * HALF + (wc * 16 + fr) * 2;
;     float sc[2][4][4];
;     _Pragma("unroll") for (int ai = 0; ai < 2; ++ai)
;       _Pragma("unroll") for (int m = 0; m < 4; ++m)
;         _Pragma("unroll") for (int j = 0; j < 4; ++j) sc[ai][m][j] = e_ss[rbase + ai * HALF + m * 16 + j];
;     _Pragma("unroll") for (int ai = 0; ai < 2; ++ai)
;       _Pragma("unroll") for (int m = 0; m < 4; ++m)
;         _Pragma("unroll") for (int j = 0; j < 4; ++j) {
;           int row = rbase + ai * HALF + m * 16 + j;
;           float s = rsqrtf(sc[ai][m][j] * (1.f / D_) + 1e-6f);
;           float h2[2];
;           _Pragma("unroll") for (int n = 0; n < 2; ++n) {
;             float a1 = acc[ai][0][m][n][j] * s, a3 = acc[ai][1][m][n][j] * s;
;             h2[n] = a1 * sigmoidf_(a1) * a3;
;           }
;           *(u32*)(e_outb + (size_t)row * F_ + oc) = pack2(h2[0], h2[1]);
;         }
.LBB0_1263:
	s_lshl_b32 s2, s87, 7
	v_ashrrev_i32_e32 v169, 31, v168
	v_lshl_or_b32 v0, v187, 1, s2
	v_lshl_add_u64 v[132:133], v[168:169], 2, s[68:69]
	v_ashrrev_i32_e32 v1, 31, v0
	v_lshl_add_u64 v[128:129], v[0:1], 1, s[90:91]
	global_load_dwordx4 v[208:211], v[132:133], off
	global_load_dwordx4 v[212:215], v[132:133], off offset:64
	global_load_dwordx4 v[216:219], v[132:133], off offset:128
	global_load_dwordx4 v[220:223], v[132:133], off offset:192
	global_load_dwordx4 v[224:227], v[132:133], off offset:512
	global_load_dwordx4 v[228:231], v[132:133], off offset:576
	global_load_dwordx4 v[232:235], v[132:133], off offset:640
	global_load_dwordx4 v[236:239], v[132:133], off offset:704
	s_movk_i32 s8, 0x2c00
	v_mad_i64_i32 v[134:135], s[2:3], v168, s8, v[128:129]
	s_mov_b32 s2, 0x358637bd
	s_nop 0
	v_mov_b64_e32 v[130:131], s[2:3]
	s_mov_b32 s12, 0x3a000000
	v_or_b32_e32 v8, 1, v168
	v_or_b32_e32 v9, 2, v168
	v_or_b32_e32 v10, 3, v168
	v_or_b32_e32 v11, 16, v168
	v_or_b32_e32 v162, 17, v168
	v_or_b32_e32 v161, 18, v168
	v_or_b32_e32 v160, 19, v168
	v_or_b32_e32 v159, 32, v168
	v_or_b32_e32 v158, 33, v168
	v_or_b32_e32 v157, 34, v168
	v_or_b32_e32 v156, 35, v168
	v_or_b32_e32 v155, 48, v168
	v_or_b32_e32 v154, 49, v168
	v_or_b32_e32 v153, 50, v168
	v_or_b32_e32 v152, 51, v168
	v_add_u32_e32 v151, 0x80, v168
	v_add_u32_e32 v150, 0x81, v168
	v_add_u32_e32 v149, 0x82, v168
	v_add_u32_e32 v148, 0x83, v168
	v_add_u32_e32 v147, 0x90, v168
	v_add_u32_e32 v146, 0x91, v168
	v_add_u32_e32 v145, 0x92, v168
	v_add_u32_e32 v144, 0x93, v168
	v_add_u32_e32 v143, 0xa0, v168
	v_add_u32_e32 v142, 0xa1, v168
	v_add_u32_e32 v141, 0xa2, v168
	v_add_u32_e32 v140, 0xa3, v168
	v_add_u32_e32 v139, 0xb0, v168
	v_add_u32_e32 v138, 0xb1, v168
	v_add_u32_e32 v137, 0xb2, v168
	v_add_u32_e32 v136, 0xb3, v168
	s_waitcnt vmcnt(0)
	v_mov_b64_e32 v[0:1], v[208:209]
	v_mov_b64_e32 v[2:3], v[210:211]
	v_pk_fma_f32 v[0:1], v[0:1], s[12:13], v[130:131] op_sel_hi:[1,0,0]
	s_nop 0
	v_pk_fma_f32 v[2:3], v[2:3], s[12:13], v[130:131] op_sel_hi:[1,0,0]
	v_rsq_f32_e32 v0, v0
	s_nop 0
	v_mul_f32_e32 v16, v116, v0
	v_mul_f32_e32 v18, 0xbfb8aa3b, v16
	v_exp_f32_e32 v18, v18
	v_mul_f32_e32 v17, v124, v0
	v_add_f32_e32 v18, 1.0, v18
	v_rcp_f32_e32 v18, v18
	s_nop 0
	v_mul_f32_e32 v16, v16, v18
	v_mul_f32_e32 v16, v17, v16
	v_mul_f32_e32 v17, v112, v0
	v_mul_f32_e32 v18, 0xbfb8aa3b, v17
	v_exp_f32_e32 v18, v18
	v_mul_f32_e32 v0, v120, v0
	v_add_f32_e32 v18, 1.0, v18
	v_rcp_f32_e32 v18, v18
	s_nop 0
	v_mul_f32_e32 v17, v17, v18
	v_mul_f32_e32 v0, v0, v17
	v_cvt_pk_bf16_f32 v0, v16, v0
	global_store_dword v[134:135], v0, off
	v_rsq_f32_e32 v0, v1
	s_nop 0
	v_mul_f32_e32 v1, v117, v0
	v_mul_f32_e32 v17, 0xbfb8aa3b, v1
	v_exp_f32_e32 v17, v17
	v_mul_f32_e32 v16, v125, v0
	v_mad_i64_i32 v[116:117], s[2:3], v11, s8, v[128:129]
	v_add_f32_e32 v17, 1.0, v17
	v_rcp_f32_e32 v17, v17
	s_nop 0
	v_mul_f32_e32 v1, v1, v17
	v_mul_f32_e32 v1, v16, v1
	v_mul_f32_e32 v16, v113, v0
	v_mul_f32_e32 v17, 0xbfb8aa3b, v16
	v_exp_f32_e32 v17, v17
	v_mul_f32_e32 v0, v121, v0
	v_add_f32_e32 v17, 1.0, v17
	v_rcp_f32_e32 v17, v17
	s_nop 0
	v_mul_f32_e32 v16, v16, v17
	v_mul_f32_e32 v0, v0, v16
	v_cvt_pk_bf16_f32 v16, v1, v0
	v_mad_i64_i32 v[0:1], s[2:3], v8, s8, v[128:129]
	v_rsq_f32_e32 v2, v2
	global_store_dword v[0:1], v16, off
	v_mad_i64_i32 v[0:1], s[2:3], v9, s8, v[128:129]
	v_mul_f32_e32 v8, v118, v2
	v_mul_f32_e32 v16, 0xbfb8aa3b, v8
	v_exp_f32_e32 v16, v16
	v_mul_f32_e32 v9, v126, v2
	v_add_f32_e32 v16, 1.0, v16
	v_rcp_f32_e32 v16, v16
	s_nop 0
	v_mul_f32_e32 v8, v8, v16
	v_mul_f32_e32 v8, v9, v8
	v_mul_f32_e32 v9, v114, v2
	v_mul_f32_e32 v16, 0xbfb8aa3b, v9
	v_exp_f32_e32 v16, v16
	v_mul_f32_e32 v2, v122, v2
	v_add_f32_e32 v16, 1.0, v16
	v_rcp_f32_e32 v16, v16
	s_nop 0
	v_mul_f32_e32 v9, v9, v16
	v_mul_f32_e32 v2, v2, v9
	v_cvt_pk_bf16_f32 v2, v8, v2
	global_store_dword v[0:1], v2, off
	v_rsq_f32_e32 v0, v3
	v_mov_b64_e32 v[16:17], v[236:237]
	v_mov_b64_e32 v[18:19], v[238:239]
	v_mul_f32_e32 v1, v119, v0
	v_mul_f32_e32 v3, 0xbfb8aa3b, v1
	v_exp_f32_e32 v3, v3
	v_mul_f32_e32 v2, v127, v0
	v_add_f32_e32 v3, 1.0, v3
	v_rcp_f32_e32 v3, v3
	s_nop 0
	v_mul_f32_e32 v1, v1, v3
	v_mul_f32_e32 v1, v2, v1
	v_mul_f32_e32 v2, v115, v0
	v_mov_b64_e32 v[112:113], v[212:213]
	v_mov_b64_e32 v[114:115], v[214:215]
	v_mul_f32_e32 v3, 0xbfb8aa3b, v2
	v_exp_f32_e32 v3, v3
	v_mul_f32_e32 v0, v123, v0
	v_add_f32_e32 v3, 1.0, v3
	v_rcp_f32_e32 v3, v3
	s_nop 0
	v_mul_f32_e32 v2, v2, v3
	v_mul_f32_e32 v0, v0, v2
	v_cvt_pk_bf16_f32 v2, v1, v0
	v_mad_i64_i32 v[0:1], s[2:3], v10, s8, v[128:129]
	global_store_dword v[0:1], v2, off
	v_pk_fma_f32 v[0:1], v[112:113], s[12:13], v[130:131] op_sel_hi:[1,0,0]
	s_nop 0
	s_nop 0
	v_rsq_f32_e32 v0, v0
	s_nop 0
	v_mul_f32_e32 v2, v100, v0
	v_mul_f32_e32 v8, 0xbfb8aa3b, v2
	v_exp_f32_e32 v8, v8
	v_mul_f32_e32 v3, v108, v0
	v_add_f32_e32 v8, 1.0, v8
	v_rcp_f32_e32 v8, v8
	s_nop 0
	v_mul_f32_e32 v2, v2, v8
	v_mul_f32_e32 v2, v3, v2
	v_mul_f32_e32 v3, v96, v0
	v_mul_f32_e32 v8, 0xbfb8aa3b, v3
	v_exp_f32_e32 v8, v8
	v_mul_f32_e32 v0, v104, v0
	v_add_f32_e32 v8, 1.0, v8
	v_rcp_f32_e32 v8, v8
	s_nop 0
	v_mul_f32_e32 v3, v3, v8
	v_mul_f32_e32 v0, v0, v3
	v_cvt_pk_bf16_f32 v0, v2, v0
	global_store_dword v[116:117], v0, off
	v_rsq_f32_e32 v0, v1
	s_nop 0
	v_mul_f32_e32 v1, v101, v0
	v_mul_f32_e32 v3, 0xbfb8aa3b, v1
	v_exp_f32_e32 v3, v3
	v_mul_f32_e32 v2, v109, v0
	v_add_f32_e32 v3, 1.0, v3
	v_rcp_f32_e32 v3, v3
	s_nop 0
	v_mul_f32_e32 v1, v1, v3
	v_mul_f32_e32 v1, v2, v1
	v_mul_f32_e32 v2, v97, v0
	v_mul_f32_e32 v3, 0xbfb8aa3b, v2
	v_exp_f32_e32 v3, v3
	v_mul_f32_e32 v0, v105, v0
; __device__ __forceinline__ u32 pack2(float a, float b) { return (u32)f2bf(a) | ((u32)f2bf(b) << 16); }
; __device__ __forceinline__ float sigmoidf_(float x) { return __builtin_amdgcn_rcpf(1.f + __expf(-x)); }
; __device__ __forceinline__ void gemm_tile(const GemmArgs& ga, int wgid, int next_wgid, bool prefetched, u16* shm, unsigned char* ws, int wv_) {
;     ...
;   if (epi == EPI_SWIGLU) {
;     const int oc = pn * HALF + (wc * 16 + fr) * 2;
;     float sc[2][4][4];
;     _Pragma("unroll") for (int ai = 0; ai < 2; ++ai)
;       _Pragma("unroll") for (int m = 0; m < 4; ++m)
;         _Pragma("unroll") for (int j = 0; j < 4; ++j) sc[ai][m][j] = e_ss[rbase + ai * HALF + m * 16 + j];
;     _Pragma("unroll") for (int ai = 0; ai < 2; ++ai)
;       _Pragma("unroll") for (int m = 0; m < 4; ++m)
;         _Pragma("unroll") for (int j = 0; j < 4; ++j) {
;           int row = rbase + ai * HALF + m * 16 + j;
;           float s = rsqrtf(sc[ai][m][j] * (1.f / D_) + 1e-6f);
;           float h2[2];
;           _Pragma("unroll") for (int n = 0; n < 2; ++n) {
;             float a1 = acc[ai][0][m][n][j] * s, a3 = acc[ai][1][m][n][j] * s;
;             h2[n] = a1 * sigmoidf_(a1) * a3;
;           }
;           *(u32*)(e_outb + (size_t)row * F_ + oc) = pack2(h2[0], h2[1]);
;         }
	v_mad_i64_i32 v[96:97], s[2:3], v159, s8, v[128:129]
	v_add_f32_e32 v3, 1.0, v3
	v_rcp_f32_e32 v3, v3
	s_nop 0
	v_mul_f32_e32 v2, v2, v3
	v_mul_f32_e32 v0, v0, v2
	v_cvt_pk_bf16_f32 v2, v1, v0
	v_mad_i64_i32 v[0:1], s[2:3], v162, s8, v[128:129]
	global_store_dword v[0:1], v2, off
	v_pk_fma_f32 v[2:3], v[114:115], s[12:13], v[130:131] op_sel_hi:[1,0,0]
	v_mad_i64_i32 v[0:1], s[2:3], v161, s8, v[128:129]
	s_nop 0
	v_rsq_f32_e32 v2, v2
	s_nop 0
	v_mul_f32_e32 v8, v102, v2
	v_mul_f32_e32 v10, 0xbfb8aa3b, v8
	v_exp_f32_e32 v10, v10
	v_mul_f32_e32 v9, v110, v2
	v_add_f32_e32 v10, 1.0, v10
	v_rcp_f32_e32 v10, v10
	s_nop 0
	v_mul_f32_e32 v8, v8, v10
	v_mul_f32_e32 v8, v9, v8
	v_mul_f32_e32 v9, v98, v2
	v_mul_f32_e32 v10, 0xbfb8aa3b, v9
	v_exp_f32_e32 v10, v10
	v_mul_f32_e32 v2, v106, v2
	v_add_f32_e32 v10, 1.0, v10
	v_rcp_f32_e32 v10, v10
	s_nop 0
	v_mul_f32_e32 v9, v9, v10
	v_mul_f32_e32 v2, v2, v9
	v_cvt_pk_bf16_f32 v2, v8, v2
	global_store_dword v[0:1], v2, off
	v_rsq_f32_e32 v0, v3
	s_nop 0
	v_mul_f32_e32 v1, v103, v0
	v_mul_f32_e32 v3, 0xbfb8aa3b, v1
	v_exp_f32_e32 v3, v3
	v_mul_f32_e32 v2, v111, v0
	v_add_f32_e32 v3, 1.0, v3
	v_rcp_f32_e32 v3, v3
	s_nop 0
	v_mul_f32_e32 v1, v1, v3
	v_mul_f32_e32 v1, v2, v1
	v_mul_f32_e32 v2, v99, v0
	v_mul_f32_e32 v3, 0xbfb8aa3b, v2
	v_exp_f32_e32 v3, v3
	v_mul_f32_e32 v0, v107, v0
	v_add_f32_e32 v3, 1.0, v3
	v_rcp_f32_e32 v3, v3
	s_nop 0
	v_mul_f32_e32 v2, v2, v3
	v_mul_f32_e32 v0, v0, v2
	v_cvt_pk_bf16_f32 v2, v1, v0
	v_mad_i64_i32 v[0:1], s[2:3], v160, s8, v[128:129]
	global_store_dword v[0:1], v2, off
	v_mov_b64_e32 v[0:1], v[216:217]
	v_mov_b64_e32 v[2:3], v[218:219]
	v_pk_fma_f32 v[0:1], v[0:1], s[12:13], v[130:131] op_sel_hi:[1,0,0]
	s_nop 0
	v_pk_fma_f32 v[2:3], v[2:3], s[12:13], v[130:131] op_sel_hi:[1,0,0]
	v_rsq_f32_e32 v0, v0
	s_nop 0
	v_mul_f32_e32 v8, v84, v0
	v_mul_f32_e32 v10, 0xbfb8aa3b, v8
	v_exp_f32_e32 v10, v10
	v_mul_f32_e32 v9, v92, v0
	v_add_f32_e32 v10, 1.0, v10
	v_rcp_f32_e32 v10, v10
	s_nop 0
	v_mul_f32_e32 v8, v8, v10
	v_mul_f32_e32 v8, v9, v8
	v_mul_f32_e32 v9, v80, v0
	v_mul_f32_e32 v10, 0xbfb8aa3b, v9
	v_exp_f32_e32 v10, v10
	v_mul_f32_e32 v0, v88, v0
	v_add_f32_e32 v10, 1.0, v10
	v_rcp_f32_e32 v10, v10
	s_nop 0
	v_mul_f32_e32 v9, v9, v10
	v_mul_f32_e32 v0, v0, v9
	v_cvt_pk_bf16_f32 v0, v8, v0
	global_store_dword v[96:97], v0, off
	v_rsq_f32_e32 v0, v1
	s_nop 0
	v_mul_f32_e32 v1, v85, v0
	v_mul_f32_e32 v9, 0xbfb8aa3b, v1
	v_exp_f32_e32 v9, v9
	v_mul_f32_e32 v8, v93, v0
	v_mad_i64_i32 v[84:85], s[2:3], v155, s8, v[128:129]
	v_add_f32_e32 v9, 1.0, v9
	v_rcp_f32_e32 v9, v9
	s_nop 0
	v_mul_f32_e32 v1, v1, v9
	v_mul_f32_e32 v1, v8, v1
	v_mul_f32_e32 v8, v81, v0
	v_mul_f32_e32 v9, 0xbfb8aa3b, v8
	v_exp_f32_e32 v9, v9
	v_mul_f32_e32 v0, v89, v0
	v_add_f32_e32 v9, 1.0, v9
	v_rcp_f32_e32 v9, v9
	s_nop 0
	v_mul_f32_e32 v8, v8, v9
	v_mul_f32_e32 v0, v0, v8
	v_cvt_pk_bf16_f32 v8, v1, v0
	v_mad_i64_i32 v[0:1], s[2:3], v158, s8, v[128:129]
	global_store_dword v[0:1], v8, off
	v_rsq_f32_e32 v2, v2
	v_mad_i64_i32 v[0:1], s[2:3], v157, s8, v[128:129]
	v_mul_f32_e32 v8, v86, v2
	v_mul_f32_e32 v10, 0xbfb8aa3b, v8
	v_exp_f32_e32 v10, v10
	v_mul_f32_e32 v9, v94, v2
	v_add_f32_e32 v10, 1.0, v10
	v_rcp_f32_e32 v10, v10
	s_nop 0
	v_mul_f32_e32 v8, v8, v10
	v_mul_f32_e32 v8, v9, v8
	v_mul_f32_e32 v9, v82, v2
	v_mul_f32_e32 v10, 0xbfb8aa3b, v9
	v_exp_f32_e32 v10, v10
	v_mul_f32_e32 v2, v90, v2
	v_add_f32_e32 v10, 1.0, v10
	v_rcp_f32_e32 v10, v10
	s_nop 0
	v_mul_f32_e32 v9, v9, v10
	v_mul_f32_e32 v2, v2, v9
	v_cvt_pk_bf16_f32 v2, v8, v2
	global_store_dword v[0:1], v2, off
	v_rsq_f32_e32 v0, v3
	s_nop 0
	v_mul_f32_e32 v1, v87, v0
	v_mul_f32_e32 v3, 0xbfb8aa3b, v1
	v_exp_f32_e32 v3, v3
	v_mul_f32_e32 v2, v95, v0
	v_add_f32_e32 v3, 1.0, v3
	v_rcp_f32_e32 v3, v3
	s_nop 0
	v_mul_f32_e32 v1, v1, v3
	v_mul_f32_e32 v1, v2, v1
	v_mul_f32_e32 v2, v83, v0
	v_mov_b64_e32 v[80:81], v[220:221]
	v_mov_b64_e32 v[82:83], v[222:223]
	v_mul_f32_e32 v3, 0xbfb8aa3b, v2
	v_exp_f32_e32 v3, v3
	v_mul_f32_e32 v0, v91, v0
	v_add_f32_e32 v3, 1.0, v3
	v_rcp_f32_e32 v3, v3
	s_nop 0
	v_mul_f32_e32 v2, v2, v3
	v_mul_f32_e32 v0, v0, v2
	v_cvt_pk_bf16_f32 v2, v1, v0
	v_mad_i64_i32 v[0:1], s[2:3], v156, s8, v[128:129]
	global_store_dword v[0:1], v2, off
	v_pk_fma_f32 v[0:1], v[80:81], s[12:13], v[130:131] op_sel_hi:[1,0,0]
	s_nop 0
	s_nop 0
	v_rsq_f32_e32 v0, v0
	s_nop 0
	v_mul_f32_e32 v2, v68, v0
	v_mul_f32_e32 v8, 0xbfb8aa3b, v2
	v_exp_f32_e32 v8, v8
	v_mul_f32_e32 v3, v76, v0
	v_add_f32_e32 v8, 1.0, v8
	v_rcp_f32_e32 v8, v8
	s_nop 0
	v_mul_f32_e32 v2, v2, v8
	v_mul_f32_e32 v2, v3, v2
	v_mul_f32_e32 v3, v64, v0
	v_mul_f32_e32 v8, 0xbfb8aa3b, v3
	v_exp_f32_e32 v8, v8
	v_mul_f32_e32 v0, v72, v0
	v_add_f32_e32 v8, 1.0, v8
	v_rcp_f32_e32 v8, v8
	s_nop 0
	v_mul_f32_e32 v3, v3, v8
	v_mul_f32_e32 v0, v0, v3
	v_cvt_pk_bf16_f32 v0, v2, v0
	global_store_dword v[84:85], v0, off
	v_rsq_f32_e32 v0, v1
	s_nop 0
	v_mul_f32_e32 v1, v69, v0
	v_mul_f32_e32 v3, 0xbfb8aa3b, v1
	v_exp_f32_e32 v3, v3
	v_mul_f32_e32 v2, v77, v0
	v_add_f32_e32 v3, 1.0, v3
	v_rcp_f32_e32 v3, v3
	s_nop 0
	v_mul_f32_e32 v1, v1, v3
	v_mul_f32_e32 v1, v2, v1
	v_mul_f32_e32 v2, v65, v0
	v_mul_f32_e32 v3, 0xbfb8aa3b, v2
	v_exp_f32_e32 v3, v3
	v_mul_f32_e32 v0, v73, v0
	v_mad_i64_i32 v[64:65], s[2:3], v151, s8, v[128:129]
	v_add_f32_e32 v3, 1.0, v3
	v_rcp_f32_e32 v3, v3
	s_nop 0
	v_mul_f32_e32 v2, v2, v3
	v_mul_f32_e32 v0, v0, v2
	v_cvt_pk_bf16_f32 v2, v1, v0
	v_mad_i64_i32 v[0:1], s[2:3], v154, s8, v[128:129]
	global_store_dword v[0:1], v2, off
	v_pk_fma_f32 v[2:3], v[82:83], s[12:13], v[130:131] op_sel_hi:[1,0,0]
	v_mad_i64_i32 v[0:1], s[2:3], v153, s8, v[128:129]
	s_nop 0
; __device__ __forceinline__ u32 pack2(float a, float b) { return (u32)f2bf(a) | ((u32)f2bf(b) << 16); }
; __device__ __forceinline__ float sigmoidf_(float x) { return __builtin_amdgcn_rcpf(1.f + __expf(-x)); }
; __device__ __forceinline__ void gemm_tile(const GemmArgs& ga, int wgid, int next_wgid, bool prefetched, u16* shm, unsigned char* ws, int wv_) {
;     ...
;   if (epi == EPI_SWIGLU) {
;     const int oc = pn * HALF + (wc * 16 + fr) * 2;
;     float sc[2][4][4];
;     _Pragma("unroll") for (int ai = 0; ai < 2; ++ai)
;       _Pragma("unroll") for (int m = 0; m < 4; ++m)
;         _Pragma("unroll") for (int j = 0; j < 4; ++j) sc[ai][m][j] = e_ss[rbase + ai * HALF + m * 16 + j];
;     _Pragma("unroll") for (int ai = 0; ai < 2; ++ai)
;       _Pragma("unroll") for (int m = 0; m < 4; ++m)
;         _Pragma("unroll") for (int j = 0; j < 4; ++j) {
;           int row = rbase + ai * HALF + m * 16 + j;
;           float s = rsqrtf(sc[ai][m][j] * (1.f / D_) + 1e-6f);
;           float h2[2];
;           _Pragma("unroll") for (int n = 0; n < 2; ++n) {
;             float a1 = acc[ai][0][m][n][j] * s, a3 = acc[ai][1][m][n][j] * s;
;             h2[n] = a1 * sigmoidf_(a1) * a3;
;           }
;           *(u32*)(e_outb + (size_t)row * F_ + oc) = pack2(h2[0], h2[1]);
;         }
	v_rsq_f32_e32 v2, v2
	s_nop 0
	v_mul_f32_e32 v8, v70, v2
	v_mul_f32_e32 v10, 0xbfb8aa3b, v8
	v_exp_f32_e32 v10, v10
	v_mul_f32_e32 v9, v78, v2
	v_add_f32_e32 v10, 1.0, v10
	v_rcp_f32_e32 v10, v10
	s_nop 0
	v_mul_f32_e32 v8, v8, v10
	v_mul_f32_e32 v8, v9, v8
	v_mul_f32_e32 v9, v66, v2
	v_mul_f32_e32 v10, 0xbfb8aa3b, v9
	v_exp_f32_e32 v10, v10
	v_mul_f32_e32 v2, v74, v2
	v_add_f32_e32 v10, 1.0, v10
	v_rcp_f32_e32 v10, v10
	s_nop 0
	v_mul_f32_e32 v9, v9, v10
	v_mul_f32_e32 v2, v2, v9
	v_cvt_pk_bf16_f32 v2, v8, v2
	global_store_dword v[0:1], v2, off
	v_rsq_f32_e32 v0, v3
	s_nop 0
	v_mul_f32_e32 v1, v71, v0
	v_mul_f32_e32 v3, 0xbfb8aa3b, v1
	v_exp_f32_e32 v3, v3
	v_mul_f32_e32 v2, v79, v0
	v_add_f32_e32 v3, 1.0, v3
	v_rcp_f32_e32 v3, v3
	s_nop 0
	v_mul_f32_e32 v1, v1, v3
	v_mul_f32_e32 v1, v2, v1
	v_mul_f32_e32 v2, v67, v0
	v_mul_f32_e32 v3, 0xbfb8aa3b, v2
	v_exp_f32_e32 v3, v3
	v_mul_f32_e32 v0, v75, v0
	v_add_f32_e32 v3, 1.0, v3
	v_rcp_f32_e32 v3, v3
	s_nop 0
	v_mul_f32_e32 v2, v2, v3
	v_mul_f32_e32 v0, v0, v2
	v_cvt_pk_bf16_f32 v2, v1, v0
	v_mad_i64_i32 v[0:1], s[2:3], v152, s8, v[128:129]
	global_store_dword v[0:1], v2, off
	v_mov_b64_e32 v[0:1], v[224:225]
	v_mov_b64_e32 v[2:3], v[226:227]
	v_pk_fma_f32 v[0:1], v[0:1], s[12:13], v[130:131] op_sel_hi:[1,0,0]
	s_nop 0
	v_pk_fma_f32 v[2:3], v[2:3], s[12:13], v[130:131] op_sel_hi:[1,0,0]
	v_rsq_f32_e32 v0, v0
	s_nop 0
	v_mul_f32_e32 v8, v52, v0
	v_mul_f32_e32 v10, 0xbfb8aa3b, v8
	v_exp_f32_e32 v10, v10
	v_mul_f32_e32 v9, v60, v0
	v_add_f32_e32 v10, 1.0, v10
	v_rcp_f32_e32 v10, v10
	s_nop 0
	v_mul_f32_e32 v8, v8, v10
	v_mul_f32_e32 v8, v9, v8
	v_mul_f32_e32 v9, v48, v0
	v_mul_f32_e32 v10, 0xbfb8aa3b, v9
	v_exp_f32_e32 v10, v10
	v_mul_f32_e32 v0, v56, v0
	v_add_f32_e32 v10, 1.0, v10
	v_rcp_f32_e32 v10, v10
	s_nop 0
	v_mul_f32_e32 v9, v9, v10
	v_mul_f32_e32 v0, v0, v9
	v_cvt_pk_bf16_f32 v0, v8, v0
	global_store_dword v[64:65], v0, off
	v_rsq_f32_e32 v0, v1
	s_nop 0
	v_mul_f32_e32 v1, v53, v0
	v_mul_f32_e32 v9, 0xbfb8aa3b, v1
	v_exp_f32_e32 v9, v9
	v_mul_f32_e32 v8, v61, v0
	v_mad_i64_i32 v[52:53], s[2:3], v147, s8, v[128:129]
	v_add_f32_e32 v9, 1.0, v9
	v_rcp_f32_e32 v9, v9
	s_nop 0
	v_mul_f32_e32 v1, v1, v9
	v_mul_f32_e32 v1, v8, v1
	v_mul_f32_e32 v8, v49, v0
	v_mul_f32_e32 v9, 0xbfb8aa3b, v8
	v_exp_f32_e32 v9, v9
	v_mul_f32_e32 v0, v57, v0
	v_add_f32_e32 v9, 1.0, v9
	v_rcp_f32_e32 v9, v9
	s_nop 0
	v_mul_f32_e32 v8, v8, v9
	v_mul_f32_e32 v0, v0, v8
	v_cvt_pk_bf16_f32 v8, v1, v0
	v_mad_i64_i32 v[0:1], s[2:3], v150, s8, v[128:129]
	global_store_dword v[0:1], v8, off
	v_rsq_f32_e32 v2, v2
	v_mad_i64_i32 v[0:1], s[2:3], v149, s8, v[128:129]
	v_mul_f32_e32 v8, v54, v2
	v_mul_f32_e32 v10, 0xbfb8aa3b, v8
	v_exp_f32_e32 v10, v10
	v_mul_f32_e32 v9, v62, v2
	v_add_f32_e32 v10, 1.0, v10
	v_rcp_f32_e32 v10, v10
	s_nop 0
	v_mul_f32_e32 v8, v8, v10
	v_mul_f32_e32 v8, v9, v8
	v_mul_f32_e32 v9, v50, v2
	v_mul_f32_e32 v10, 0xbfb8aa3b, v9
	v_exp_f32_e32 v10, v10
	v_mul_f32_e32 v2, v58, v2
	v_add_f32_e32 v10, 1.0, v10
	v_rcp_f32_e32 v10, v10
	s_nop 0
	v_mul_f32_e32 v9, v9, v10
	v_mul_f32_e32 v2, v2, v9
	v_cvt_pk_bf16_f32 v2, v8, v2
	global_store_dword v[0:1], v2, off
	v_rsq_f32_e32 v0, v3
	s_nop 0
	v_mul_f32_e32 v1, v55, v0
	v_mul_f32_e32 v3, 0xbfb8aa3b, v1
	v_exp_f32_e32 v3, v3
	v_mul_f32_e32 v2, v63, v0
	v_add_f32_e32 v3, 1.0, v3
	v_rcp_f32_e32 v3, v3
	s_nop 0
	v_mul_f32_e32 v1, v1, v3
	v_mul_f32_e32 v1, v2, v1
	v_mul_f32_e32 v2, v51, v0
	v_mov_b64_e32 v[48:49], v[228:229]
	v_mov_b64_e32 v[50:51], v[230:231]
	v_mul_f32_e32 v3, 0xbfb8aa3b, v2
	v_exp_f32_e32 v3, v3
	v_mul_f32_e32 v0, v59, v0
	v_add_f32_e32 v3, 1.0, v3
	v_rcp_f32_e32 v3, v3
	s_nop 0
	v_mul_f32_e32 v2, v2, v3
	v_mul_f32_e32 v0, v0, v2
	v_cvt_pk_bf16_f32 v2, v1, v0
	v_mad_i64_i32 v[0:1], s[2:3], v148, s8, v[128:129]
	global_store_dword v[0:1], v2, off
	v_pk_fma_f32 v[0:1], v[48:49], s[12:13], v[130:131] op_sel_hi:[1,0,0]
	s_nop 0
	s_nop 0
	v_rsq_f32_e32 v0, v0
	s_nop 0
	v_mul_f32_e32 v2, v36, v0
	v_mul_f32_e32 v8, 0xbfb8aa3b, v2
	v_exp_f32_e32 v8, v8
	v_mul_f32_e32 v3, v44, v0
	v_add_f32_e32 v8, 1.0, v8
	v_rcp_f32_e32 v8, v8
	s_nop 0
	v_mul_f32_e32 v2, v2, v8
	v_mul_f32_e32 v2, v3, v2
	v_mul_f32_e32 v3, v32, v0
	v_mul_f32_e32 v8, 0xbfb8aa3b, v3
	v_exp_f32_e32 v8, v8
	v_mul_f32_e32 v0, v40, v0
	v_add_f32_e32 v8, 1.0, v8
	v_rcp_f32_e32 v8, v8
	s_nop 0
	v_mul_f32_e32 v3, v3, v8
	v_mul_f32_e32 v0, v0, v3
	v_cvt_pk_bf16_f32 v0, v2, v0
	global_store_dword v[52:53], v0, off
	v_rsq_f32_e32 v0, v1
	s_nop 0
	v_mul_f32_e32 v1, v37, v0
	v_mul_f32_e32 v3, 0xbfb8aa3b, v1
	v_exp_f32_e32 v3, v3
	v_mul_f32_e32 v2, v45, v0
	v_add_f32_e32 v3, 1.0, v3
	v_rcp_f32_e32 v3, v3
	s_nop 0
	v_mul_f32_e32 v1, v1, v3
	v_mul_f32_e32 v1, v2, v1
	v_mul_f32_e32 v2, v33, v0
	v_mul_f32_e32 v3, 0xbfb8aa3b, v2
	v_exp_f32_e32 v3, v3
	v_mul_f32_e32 v0, v41, v0
	v_mad_i64_i32 v[32:33], s[2:3], v143, s8, v[128:129]
	v_add_f32_e32 v3, 1.0, v3
	v_rcp_f32_e32 v3, v3
	s_nop 0
	v_mul_f32_e32 v2, v2, v3
	v_mul_f32_e32 v0, v0, v2
	v_cvt_pk_bf16_f32 v2, v1, v0
	v_mad_i64_i32 v[0:1], s[2:3], v146, s8, v[128:129]
	global_store_dword v[0:1], v2, off
	v_pk_fma_f32 v[2:3], v[50:51], s[12:13], v[130:131] op_sel_hi:[1,0,0]
	v_mad_i64_i32 v[0:1], s[2:3], v145, s8, v[128:129]
	s_nop 0
	v_rsq_f32_e32 v2, v2
	s_nop 0
	v_mul_f32_e32 v8, v38, v2
	v_mul_f32_e32 v10, 0xbfb8aa3b, v8
	v_exp_f32_e32 v10, v10
	v_mul_f32_e32 v9, v46, v2
	v_add_f32_e32 v10, 1.0, v10
	v_rcp_f32_e32 v10, v10
	s_nop 0
	v_mul_f32_e32 v8, v8, v10
	v_mul_f32_e32 v8, v9, v8
	v_mul_f32_e32 v9, v34, v2
	v_mul_f32_e32 v10, 0xbfb8aa3b, v9
	v_exp_f32_e32 v10, v10
	v_mul_f32_e32 v2, v42, v2
	v_add_f32_e32 v10, 1.0, v10
	v_rcp_f32_e32 v10, v10
; __device__ __forceinline__ u32 pack2(float a, float b) { return (u32)f2bf(a) | ((u32)f2bf(b) << 16); }
; __device__ __forceinline__ float sigmoidf_(float x) { return __builtin_amdgcn_rcpf(1.f + __expf(-x)); }
; __device__ __forceinline__ void gemm_tile(const GemmArgs& ga, int wgid, int next_wgid, bool prefetched, u16* shm, unsigned char* ws, int wv_) {
;     ...
;   if (epi == EPI_SWIGLU) {
;     const int oc = pn * HALF + (wc * 16 + fr) * 2;
;     float sc[2][4][4];
;     _Pragma("unroll") for (int ai = 0; ai < 2; ++ai)
;       _Pragma("unroll") for (int m = 0; m < 4; ++m)
;         _Pragma("unroll") for (int j = 0; j < 4; ++j) sc[ai][m][j] = e_ss[rbase + ai * HALF + m * 16 + j];
;     _Pragma("unroll") for (int ai = 0; ai < 2; ++ai)
;       _Pragma("unroll") for (int m = 0; m < 4; ++m)
;         _Pragma("unroll") for (int j = 0; j < 4; ++j) {
;           int row = rbase + ai * HALF + m * 16 + j;
;           float s = rsqrtf(sc[ai][m][j] * (1.f / D_) + 1e-6f);
;           float h2[2];
;           _Pragma("unroll") for (int n = 0; n < 2; ++n) {
;             float a1 = acc[ai][0][m][n][j] * s, a3 = acc[ai][1][m][n][j] * s;
;             h2[n] = a1 * sigmoidf_(a1) * a3;
;           }
;           *(u32*)(e_outb + (size_t)row * F_ + oc) = pack2(h2[0], h2[1]);
;         }
	s_nop 0
	v_mul_f32_e32 v9, v9, v10
	v_mul_f32_e32 v2, v2, v9
	v_cvt_pk_bf16_f32 v2, v8, v2
	global_store_dword v[0:1], v2, off
	v_rsq_f32_e32 v0, v3
	s_nop 0
	v_mul_f32_e32 v1, v39, v0
	v_mul_f32_e32 v3, 0xbfb8aa3b, v1
	v_exp_f32_e32 v3, v3
	v_mul_f32_e32 v2, v47, v0
	v_add_f32_e32 v3, 1.0, v3
	v_rcp_f32_e32 v3, v3
	s_nop 0
	v_mul_f32_e32 v1, v1, v3
	v_mul_f32_e32 v1, v2, v1
	v_mul_f32_e32 v2, v35, v0
	v_mul_f32_e32 v3, 0xbfb8aa3b, v2
	v_exp_f32_e32 v3, v3
	v_mul_f32_e32 v0, v43, v0
	v_add_f32_e32 v3, 1.0, v3
	v_rcp_f32_e32 v3, v3
	s_nop 0
	v_mul_f32_e32 v2, v2, v3
	v_mul_f32_e32 v0, v0, v2
	v_cvt_pk_bf16_f32 v2, v1, v0
	v_mad_i64_i32 v[0:1], s[2:3], v144, s8, v[128:129]
	global_store_dword v[0:1], v2, off
	v_mov_b64_e32 v[0:1], v[232:233]
	v_mov_b64_e32 v[2:3], v[234:235]
	v_pk_fma_f32 v[0:1], v[0:1], s[12:13], v[130:131] op_sel_hi:[1,0,0]
	s_nop 0
	v_pk_fma_f32 v[2:3], v[2:3], s[12:13], v[130:131] op_sel_hi:[1,0,0]
	v_rsq_f32_e32 v0, v0
	s_nop 0
	v_mul_f32_e32 v8, v20, v0
	v_mul_f32_e32 v10, 0xbfb8aa3b, v8
	v_exp_f32_e32 v10, v10
	v_mul_f32_e32 v9, v244, v0
	v_add_f32_e32 v10, 1.0, v10
	v_rcp_f32_e32 v10, v10
	s_nop 0
	v_mul_f32_e32 v8, v8, v10
	v_mul_f32_e32 v8, v9, v8
	v_mul_f32_e32 v9, v240, v0
	v_mul_f32_e32 v10, 0xbfb8aa3b, v9
	v_exp_f32_e32 v10, v10
	v_mul_f32_e32 v0, v24, v0
	v_add_f32_e32 v10, 1.0, v10
	v_rcp_f32_e32 v10, v10
	s_nop 0
	v_mul_f32_e32 v9, v9, v10
	v_mul_f32_e32 v0, v0, v9
	v_cvt_pk_bf16_f32 v0, v8, v0
	global_store_dword v[32:33], v0, off
	v_rsq_f32_e32 v0, v1
	s_nop 0
	v_mul_f32_e32 v1, v21, v0
	v_mul_f32_e32 v9, 0xbfb8aa3b, v1
	v_exp_f32_e32 v9, v9
	v_mul_f32_e32 v8, v245, v0
	v_mad_i64_i32 v[20:21], s[2:3], v139, s8, v[128:129]
	v_add_f32_e32 v9, 1.0, v9
	v_rcp_f32_e32 v9, v9
	s_nop 0
	v_mul_f32_e32 v1, v1, v9
	v_mul_f32_e32 v1, v8, v1
	v_mul_f32_e32 v8, v241, v0
	v_mul_f32_e32 v9, 0xbfb8aa3b, v8
	v_exp_f32_e32 v9, v9
	v_mul_f32_e32 v0, v25, v0
	v_add_f32_e32 v9, 1.0, v9
	v_rcp_f32_e32 v9, v9
	s_nop 0
	v_mul_f32_e32 v8, v8, v9
	v_mul_f32_e32 v0, v0, v8
	v_cvt_pk_bf16_f32 v8, v1, v0
	v_mad_i64_i32 v[0:1], s[2:3], v142, s8, v[128:129]
	global_store_dword v[0:1], v8, off
	v_rsq_f32_e32 v2, v2
	v_mad_i64_i32 v[0:1], s[2:3], v141, s8, v[128:129]
	v_mul_f32_e32 v8, v22, v2
	v_mul_f32_e32 v10, 0xbfb8aa3b, v8
	v_exp_f32_e32 v10, v10
	v_mul_f32_e32 v9, v246, v2
	v_add_f32_e32 v10, 1.0, v10
	v_rcp_f32_e32 v10, v10
	s_nop 0
	v_mul_f32_e32 v8, v8, v10
	v_mul_f32_e32 v8, v9, v8
	v_mul_f32_e32 v9, v242, v2
	v_mul_f32_e32 v10, 0xbfb8aa3b, v9
	v_exp_f32_e32 v10, v10
	v_mul_f32_e32 v2, v26, v2
	v_add_f32_e32 v10, 1.0, v10
	v_rcp_f32_e32 v10, v10
	s_nop 0
	v_mul_f32_e32 v9, v9, v10
	v_mul_f32_e32 v2, v2, v9
	v_cvt_pk_bf16_f32 v2, v8, v2
	global_store_dword v[0:1], v2, off
	v_rsq_f32_e32 v0, v3
	s_nop 0
	v_mul_f32_e32 v1, v23, v0
	v_mul_f32_e32 v3, 0xbfb8aa3b, v1
	v_exp_f32_e32 v3, v3
	v_mul_f32_e32 v2, v247, v0
	v_add_f32_e32 v3, 1.0, v3
	v_rcp_f32_e32 v3, v3
	s_nop 0
	v_mul_f32_e32 v1, v1, v3
	v_mul_f32_e32 v1, v2, v1
	v_mul_f32_e32 v2, v243, v0
	v_mul_f32_e32 v3, 0xbfb8aa3b, v2
	v_exp_f32_e32 v3, v3
	v_mul_f32_e32 v0, v27, v0
	v_add_f32_e32 v3, 1.0, v3
	v_rcp_f32_e32 v3, v3
	s_nop 0
	v_mul_f32_e32 v2, v2, v3
	v_mul_f32_e32 v0, v0, v2
	v_cvt_pk_bf16_f32 v2, v1, v0
	v_mad_i64_i32 v[0:1], s[2:3], v140, s8, v[128:129]
	global_store_dword v[0:1], v2, off
	v_pk_fma_f32 v[0:1], v[16:17], s[12:13], v[130:131] op_sel_hi:[1,0,0]
	s_nop 0
	s_nop 0
	v_rsq_f32_e32 v0, v0
	s_nop 0
	v_mul_f32_e32 v2, v204, v0
	v_mul_f32_e32 v8, 0xbfb8aa3b, v2
	v_exp_f32_e32 v8, v8
	v_mul_f32_e32 v3, v12, v0
	v_add_f32_e32 v8, 1.0, v8
	v_rcp_f32_e32 v8, v8
	s_nop 0
	v_mul_f32_e32 v2, v2, v8
	v_mul_f32_e32 v2, v3, v2
	v_mul_f32_e32 v3, v182, v0
	v_mul_f32_e32 v0, v4, v0
	v_mul_f32_e32 v4, 0xbfb8aa3b, v3
	v_exp_f32_e32 v4, v4
	s_nop 0
	v_add_f32_e32 v4, 1.0, v4
	v_rcp_f32_e32 v4, v4
	s_nop 0
	v_mul_f32_e32 v3, v3, v4
	v_mul_f32_e32 v0, v0, v3
	v_cvt_pk_bf16_f32 v0, v2, v0
	global_store_dword v[20:21], v0, off
	v_rsq_f32_e32 v0, v1
	s_nop 0
	v_mul_f32_e32 v1, v205, v0
	v_mul_f32_e32 v3, 0xbfb8aa3b, v1
	v_exp_f32_e32 v3, v3
	v_mul_f32_e32 v2, v13, v0
	v_add_f32_e32 v3, 1.0, v3
	v_rcp_f32_e32 v3, v3
	s_nop 0
	v_mul_f32_e32 v1, v1, v3
	v_mul_f32_e32 v1, v2, v1
	v_mul_f32_e32 v2, v183, v0
	v_mul_f32_e32 v3, 0xbfb8aa3b, v2
	v_exp_f32_e32 v3, v3
	v_mul_f32_e32 v0, v5, v0
	v_add_f32_e32 v3, 1.0, v3
	v_rcp_f32_e32 v3, v3
	s_nop 0
	v_mul_f32_e32 v2, v2, v3
	v_mul_f32_e32 v0, v0, v2
	v_cvt_pk_bf16_f32 v2, v1, v0
	v_mad_i64_i32 v[0:1], s[2:3], v138, s8, v[128:129]
	global_store_dword v[0:1], v2, off
	v_pk_fma_f32 v[2:3], v[18:19], s[12:13], v[130:131] op_sel_hi:[1,0,0]
	v_mad_i64_i32 v[0:1], s[2:3], v137, s8, v[128:129]
	s_nop 0
	v_rsq_f32_e32 v2, v2
	s_nop 0
	v_mul_f32_e32 v4, v206, v2
	v_mul_f32_e32 v8, 0xbfb8aa3b, v4
	v_exp_f32_e32 v8, v8
	v_mul_f32_e32 v5, v14, v2
	v_add_f32_e32 v8, 1.0, v8
	v_rcp_f32_e32 v8, v8
	s_nop 0
	v_mul_f32_e32 v4, v4, v8
	v_mul_f32_e32 v4, v5, v4
	v_mul_f32_e32 v5, v184, v2
	v_mul_f32_e32 v2, v6, v2
	v_mul_f32_e32 v6, 0xbfb8aa3b, v5
	v_exp_f32_e32 v6, v6
	s_nop 0
	v_add_f32_e32 v6, 1.0, v6
	v_rcp_f32_e32 v6, v6
	s_nop 0
	v_mul_f32_e32 v5, v5, v6
	v_mul_f32_e32 v2, v2, v5
	v_cvt_pk_bf16_f32 v2, v4, v2
	global_store_dword v[0:1], v2, off
	v_rsq_f32_e32 v0, v3
	s_nop 0
	v_mul_f32_e32 v1, v207, v0
	v_mul_f32_e32 v3, 0xbfb8aa3b, v1
	v_exp_f32_e32 v3, v3
	v_mul_f32_e32 v2, v15, v0
	v_add_f32_e32 v3, 1.0, v3
	v_rcp_f32_e32 v3, v3
	s_nop 0
	v_mul_f32_e32 v1, v1, v3
	v_mul_f32_e32 v1, v2, v1
	v_mul_f32_e32 v2, v185, v0
	v_mul_f32_e32 v3, 0xbfb8aa3b, v2
	v_exp_f32_e32 v3, v3
	v_mul_f32_e32 v0, v7, v0
	v_add_f32_e32 v3, 1.0, v3
	v_rcp_f32_e32 v3, v3
	s_nop 0
	v_mul_f32_e32 v2, v2, v3
	v_mul_f32_e32 v0, v0, v2
	v_bfe_u32 v2, v1, 16, 1
	v_add3_u32 v1, v1, v2, s48
	v_bfe_u32 v2, v0, 16, 1
	v_lshrrev_b32_e32 v1, 16, v1
	v_add3_u32 v0, v0, v2, s48
	v_and_or_b32 v2, v0, s97, v1
	v_mad_i64_i32 v[0:1], s[2:3], v136, s8, v[128:129]
	global_store_dword v[0:1], v2, off
	s_branch .LBB0_501
